# v24 plus v_permlane16_swap instead of ds_swizzle in the indexer select-loop count reduction
# speedup vs baseline: 1.0020x; 1.0020x over previous
.Lidxsel_sum:
	v_add3_u32 v6, v6, v7, v8
	s_nop 1
	v_add_u32_dpp v6, v6, v6 quad_perm:[1,0,3,2] row_mask:0xf bank_mask:0xf
	s_nop 1
	v_add_u32_dpp v6, v6, v6 quad_perm:[2,3,0,1] row_mask:0xf bank_mask:0xf
	s_nop 1
	v_add_u32_dpp v6, v6, v6 row_ror:4 row_mask:0xf bank_mask:0xf
	s_nop 1
	v_add_u32_dpp v6, v6, v6 row_ror:8 row_mask:0xf bank_mask:0xf
	v_mov_b32_e32 v7, v6
	s_nop 1
	v_permlane16_swap_b32_e32 v7, v6
	v_add_u32_e32 v6, v6, v7
	v_cmp_gt_i32_e32 vcc, s33, v6
	s_or_b64 vcc, s[74:75], vcc
	v_cmp_eq_u32_e64 s[74:75], s33, v6
	v_cndmask_b32_e32 v66, v5, v66, vcc
	s_nop 0
	v_cndmask_b32_e64 v5, 0, 1, s[74:75]
	v_cndmask_b32_e32 v4, v5, v4, vcc
	v_and_b32_e32 v4, 1, v4
	v_cmp_eq_u32_e64 s[82:83], 1, v4
	v_cmp_eq_u32_e32 vcc, -1, v2
